# merge GEMM (half-M): removed the duplicate A-half LDS-DMA stages (2 of 8 per iteration), vmcnt guarantees unchanged
# speedup vs baseline: 1.0248x; 1.0098x over previous
.LBB0_307:
	s_add_i32 s64, s8, 2
	s_add_u32 s9, s2, 0x80
	s_addc_u32 s24, s3, 0
	s_add_i32 s30, 0, 0x10000
	v_add_u32_e32 v82, s30, v179
	ds_read_b128 v[54:57], v82
	ds_read_b128 v[66:69], v82 offset:1024
	ds_read_b128 v[78:81], v82 offset:2048
	ds_read_b128 v[82:85], v82 offset:3072
	s_cmp_eq_u32 s47, s8
	s_cselect_b32 s8, s46, s62
	s_cselect_b32 s25, s13, s24
	s_cselect_b32 s24, s35, s9
	s_cselect_b32 s9, s41, s63
	ds_read_b128 v[86:89], v181
	ds_read_b128 v[90:93], v181 offset:1024
	ds_read_b128 v[94:97], v181 offset:2048
	ds_read_b128 v[170:173], v181 offset:3072
	ds_read_b128 v[174:177], v181 offset:4096
	ds_read_b128 v[182:185], v181 offset:5120
	ds_read_b128 v[186:189], v181 offset:6144
	ds_read_b128 v[190:193], v181 offset:7168
	s_waitcnt lgkmcnt(8)
	s_barrier
	s_waitcnt lgkmcnt(0)
	s_setprio 1
	s_waitcnt lgkmcnt(0)
	v_mfma_f32_16x16x32_bf16 v[74:77], v[54:57], v[86:89], v[74:77]
	v_mfma_f32_16x16x32_bf16 v[70:73], v[78:81], v[86:89], v[70:73]
	v_mfma_f32_16x16x32_bf16 v[50:53], v[54:57], v[94:97], v[50:53]
	v_mfma_f32_16x16x32_bf16 v[46:49], v[78:81], v[94:97], v[46:49]
	v_mfma_f32_16x16x32_bf16 v[34:37], v[54:57], v[174:177], v[34:37]
	v_mfma_f32_16x16x32_bf16 v[30:33], v[78:81], v[174:177], v[30:33]
	v_mfma_f32_16x16x32_bf16 v[18:21], v[54:57], v[186:189], v[18:21]
	v_mfma_f32_16x16x32_bf16 v[14:17], v[78:81], v[186:189], v[14:17]
	v_mfma_f32_16x16x32_bf16 v[74:77], v[66:69], v[90:93], v[74:77]
	v_mfma_f32_16x16x32_bf16 v[70:73], v[82:85], v[90:93], v[70:73]
	v_mfma_f32_16x16x32_bf16 v[50:53], v[66:69], v[170:173], v[50:53]
	v_mfma_f32_16x16x32_bf16 v[46:49], v[82:85], v[170:173], v[46:49]
	v_mfma_f32_16x16x32_bf16 v[34:37], v[66:69], v[182:185], v[34:37]
	v_mfma_f32_16x16x32_bf16 v[30:33], v[82:85], v[182:185], v[30:33]
	v_mfma_f32_16x16x32_bf16 v[18:21], v[66:69], v[190:193], v[18:21]
	v_mfma_f32_16x16x32_bf16 v[14:17], v[82:85], v[190:193], v[14:17]
	s_setprio 0
	s_barrier
	s_add_i32 s31, 0, 0x14000
	s_add_i32 s30, s30, s53
	v_add_u32_e32 v82, s31, v179
	v_lshl_add_u64 v[196:197], s[8:9], 0, v[194:195]
	s_mov_b32 m0, s30
	ds_read_b128 v[54:57], v82
	ds_read_b128 v[66:69], v82 offset:1024
	ds_read_b128 v[78:81], v82 offset:2048
	ds_read_b128 v[82:85], v82 offset:3072
	global_load_lds_dwordx4 v[196:197], off
	v_lshl_add_u64 v[200:201], s[8:9], 0, v[8:9]
	s_add_i32 m0, s30, 0x2000
	s_nop 0
	global_load_lds_dwordx4 v[200:201], off
	s_barrier
	s_waitcnt lgkmcnt(0)
	s_setprio 1
	s_waitcnt lgkmcnt(0)
	v_mfma_f32_16x16x32_bf16 v[62:65], v[54:57], v[86:89], v[62:65]
	v_mfma_f32_16x16x32_bf16 v[58:61], v[78:81], v[86:89], v[58:61]
	v_mfma_f32_16x16x32_bf16 v[42:45], v[54:57], v[94:97], v[42:45]
	v_mfma_f32_16x16x32_bf16 v[38:41], v[78:81], v[94:97], v[38:41]
	v_mfma_f32_16x16x32_bf16 v[26:29], v[54:57], v[174:177], v[26:29]
	v_mfma_f32_16x16x32_bf16 v[22:25], v[78:81], v[174:177], v[22:25]
	v_mfma_f32_16x16x32_bf16 v[4:7], v[54:57], v[186:189], v[4:7]
	v_mfma_f32_16x16x32_bf16 v[0:3], v[78:81], v[186:189], v[0:3]
	v_mfma_f32_16x16x32_bf16 v[62:65], v[66:69], v[90:93], v[62:65]
	v_mfma_f32_16x16x32_bf16 v[58:61], v[82:85], v[90:93], v[58:61]
	v_mfma_f32_16x16x32_bf16 v[42:45], v[66:69], v[170:173], v[42:45]
	v_mfma_f32_16x16x32_bf16 v[38:41], v[82:85], v[170:173], v[38:41]
	v_mfma_f32_16x16x32_bf16 v[26:29], v[66:69], v[182:185], v[26:29]
	v_mfma_f32_16x16x32_bf16 v[22:25], v[82:85], v[182:185], v[22:25]
	v_mfma_f32_16x16x32_bf16 v[4:7], v[66:69], v[190:193], v[4:7]
	v_mfma_f32_16x16x32_bf16 v[0:3], v[82:85], v[190:193], v[0:3]
	s_setprio 0
	s_mov_b32 m0, s54
	v_lshl_add_u64 v[202:203], s[24:25], 0, v[100:101]
	s_barrier
	global_load_lds_dwordx4 v[202:203], off
	v_lshl_add_u64 v[204:205], s[24:25], 0, v[98:99]
	s_mov_b32 m0, s19
	s_nop 0
	global_load_lds_dwordx4 v[204:205], off
	s_barrier
	s_waitcnt lgkmcnt(0)
	s_barrier
	s_add_u32 s24, s8, 0x80000
	s_addc_u32 s25, s9, 0
	s_add_i32 s30, s31, s53
	v_lshl_add_u64 v[54:55], s[24:25], 0, v[194:195]
	s_mov_b32 m0, s30
	s_nop 0
	global_load_lds_dwordx4 v[54:55], off
	v_lshl_add_u64 v[54:55], s[24:25], 0, v[8:9]
	s_add_i32 m0, s30, 0x2000
	s_add_i32 s24, 0, 0x18000
	global_load_lds_dwordx4 v[54:55], off
	v_add_u32_e32 v82, s24, v179
	s_waitcnt vmcnt(6)
	s_barrier
	s_barrier
	ds_read_b128 v[54:57], v82
	ds_read_b128 v[66:69], v82 offset:1024
	ds_read_b128 v[78:81], v82 offset:2048
	ds_read_b128 v[82:85], v82 offset:3072
	ds_read_b128 v[86:89], v181 offset:32768
	ds_read_b128 v[90:93], v181 offset:33792
	ds_read_b128 v[94:97], v181 offset:34816
	ds_read_b128 v[170:173], v181 offset:35840
	ds_read_b128 v[174:177], v181 offset:36864
	ds_read_b128 v[182:185], v181 offset:37888
	ds_read_b128 v[186:189], v181 offset:38912
	ds_read_b128 v[190:193], v181 offset:39936
	s_waitcnt lgkmcnt(8)
	s_barrier
	s_waitcnt lgkmcnt(0)
	s_setprio 1
	s_waitcnt lgkmcnt(0)
	v_mfma_f32_16x16x32_bf16 v[74:77], v[54:57], v[86:89], v[74:77]
	v_mfma_f32_16x16x32_bf16 v[70:73], v[78:81], v[86:89], v[70:73]
	v_mfma_f32_16x16x32_bf16 v[50:53], v[54:57], v[94:97], v[50:53]
	v_mfma_f32_16x16x32_bf16 v[46:49], v[78:81], v[94:97], v[46:49]
	v_mfma_f32_16x16x32_bf16 v[34:37], v[54:57], v[174:177], v[34:37]
	v_mfma_f32_16x16x32_bf16 v[30:33], v[78:81], v[174:177], v[30:33]
	v_mfma_f32_16x16x32_bf16 v[18:21], v[54:57], v[186:189], v[18:21]
	v_mfma_f32_16x16x32_bf16 v[14:17], v[78:81], v[186:189], v[14:17]
	v_mfma_f32_16x16x32_bf16 v[74:77], v[66:69], v[90:93], v[74:77]
	v_mfma_f32_16x16x32_bf16 v[70:73], v[82:85], v[90:93], v[70:73]
	v_mfma_f32_16x16x32_bf16 v[50:53], v[66:69], v[170:173], v[50:53]
	v_mfma_f32_16x16x32_bf16 v[46:49], v[82:85], v[170:173], v[46:49]
	v_mfma_f32_16x16x32_bf16 v[34:37], v[66:69], v[182:185], v[34:37]
	v_mfma_f32_16x16x32_bf16 v[30:33], v[82:85], v[182:185], v[30:33]
	v_mfma_f32_16x16x32_bf16 v[18:21], v[66:69], v[190:193], v[18:21]
	v_mfma_f32_16x16x32_bf16 v[14:17], v[82:85], v[190:193], v[14:17]
	s_setprio 0
	s_barrier
	s_add_i32 s25, 0, 0x1c000
	s_add_i32 s24, s24, s53
	v_add_u32_e32 v82, s25, v179
	v_lshl_add_u64 v[196:197], v[196:197], 0, s[22:23]
	s_mov_b32 m0, s24
	ds_read_b128 v[54:57], v82
	ds_read_b128 v[66:69], v82 offset:1024
	ds_read_b128 v[78:81], v82 offset:2048
	ds_read_b128 v[82:85], v82 offset:3072
	global_load_lds_dwordx4 v[196:197], off
	v_lshl_add_u64 v[196:197], v[200:201], 0, s[22:23]
	s_add_i32 m0, s24, 0x2000
	s_nop 0
	global_load_lds_dwordx4 v[196:197], off
	s_barrier
	s_waitcnt lgkmcnt(0)
	s_setprio 1
	s_waitcnt lgkmcnt(0)
	v_mfma_f32_16x16x32_bf16 v[62:65], v[54:57], v[86:89], v[62:65]
	v_mfma_f32_16x16x32_bf16 v[58:61], v[78:81], v[86:89], v[58:61]
	v_mfma_f32_16x16x32_bf16 v[42:45], v[54:57], v[94:97], v[42:45]
	v_mfma_f32_16x16x32_bf16 v[38:41], v[78:81], v[94:97], v[38:41]
	v_mfma_f32_16x16x32_bf16 v[26:29], v[54:57], v[174:177], v[26:29]
	v_mfma_f32_16x16x32_bf16 v[22:25], v[78:81], v[174:177], v[22:25]
	v_mfma_f32_16x16x32_bf16 v[4:7], v[54:57], v[186:189], v[4:7]
	v_mfma_f32_16x16x32_bf16 v[0:3], v[78:81], v[186:189], v[0:3]
	v_mfma_f32_16x16x32_bf16 v[62:65], v[66:69], v[90:93], v[62:65]
	v_mfma_f32_16x16x32_bf16 v[58:61], v[82:85], v[90:93], v[58:61]
	v_mfma_f32_16x16x32_bf16 v[42:45], v[66:69], v[170:173], v[42:45]
	v_mfma_f32_16x16x32_bf16 v[38:41], v[82:85], v[170:173], v[38:41]
	v_mfma_f32_16x16x32_bf16 v[26:29], v[66:69], v[182:185], v[26:29]
	v_mfma_f32_16x16x32_bf16 v[22:25], v[82:85], v[182:185], v[22:25]
	v_mfma_f32_16x16x32_bf16 v[4:7], v[66:69], v[190:193], v[4:7]
	v_mfma_f32_16x16x32_bf16 v[0:3], v[82:85], v[190:193], v[0:3]
	s_setprio 0
	s_mov_b32 m0, s55
	v_lshl_add_u64 v[54:55], v[202:203], 0, s[22:23]
	s_barrier
	global_load_lds_dwordx4 v[54:55], off
	v_lshl_add_u64 v[54:55], v[204:205], 0, s[22:23]
	s_mov_b32 m0, s56
	s_nop 0
	global_load_lds_dwordx4 v[54:55], off
	s_barrier
	s_waitcnt lgkmcnt(0)
	s_barrier
	s_add_u32 s8, s8, 0x80080
	s_addc_u32 s9, s9, 0
	s_add_i32 s24, s25, s53
	v_lshl_add_u64 v[54:55], s[8:9], 0, v[194:195]
	s_mov_b32 m0, s24
	s_nop 0
	global_load_lds_dwordx4 v[54:55], off
	v_lshl_add_u64 v[54:55], s[8:9], 0, v[8:9]
	s_add_i32 m0, s24, 0x2000
	s_add_u32 s2, s2, 0x100
	global_load_lds_dwordx4 v[54:55], off
	s_addc_u32 s3, s3, 0
	s_waitcnt vmcnt(6)
	s_add_u32 s62, s62, 0x100
	s_addc_u32 s63, s63, 0
	s_cmp_ge_i32 s64, s7
	s_mov_b32 s8, s64
	s_barrier
	s_barrier
	s_cbranch_scc0 .LBB0_307
	s_branch .LBB0_309
